# workgroups with id bit 3 set run the out-projection GEMM before the gate/up weight transposes (other half keeps the order): HBM-bound transposes overlap the other half's MFMA-bound GEMM
# speedup vs baseline: 1.0067x; 1.0009x over previous
.LBB0_707:
	s_add_u32 s88, s66, 0xa000000
	s_addc_u32 s89, s67, 0
	v_mov_b32_e32 v66, v174
	s_cmp_gt_i32 s80, 0xafff
	s_waitcnt lgkmcnt(0)
	s_barrier
	s_bfe_u32 s69, s87, 0x10003
	s_cmp_eq_u32 s69, 1
	s_cbranch_scc1 .LBB0_712
	s_cmp_gt_i32 s80, 0xafff
	s_cbranch_scc1 .LBB0_712
.Lguw_entry:
	s_waitcnt vmcnt(0)
	v_ashrrev_i32_e32 v69, 5, v66
	s_lshl_b32 s0, s72, 14
	s_movk_i32 s5, 0x2c00
	v_add_u32_e32 v16, 2, v69
	v_add_u32_e32 v18, 4, v69
	v_add_u32_e32 v20, 6, v69
	v_add_u32_e32 v22, 8, v69
	s_add_i32 s4, s0, 0
	v_mad_i64_i32 v[2:3], s[0:1], v69, s5, 0
	v_mad_i64_i32 v[4:5], s[0:1], v16, s5, 0
	v_mad_i64_i32 v[6:7], s[0:1], v18, s5, 0
	v_mad_i64_i32 v[8:9], s[0:1], v20, s5, 0
	v_mad_i64_i32 v[10:11], s[0:1], v22, s5, 0
	s_mul_hi_i32 s0, s80, 0x2e8ba2e9
	s_lshr_b32 s1, s0, 31
	s_ashr_i32 s0, s0, 9
	s_add_i32 s9, s0, s1
	s_mul_i32 s0, s9, 0xb00
	s_sub_i32 s8, s80, s0
	s_cmpk_gt_i32 s8, 0x57f
	s_cselect_b64 s[6:7], -1, 0
	s_add_i32 s10, s8, 0xfa80
	s_and_b64 s[0:1], s[6:7], exec
	s_cselect_b32 s0, s10, s8
	s_sext_i32_i16 s1, s0
	s_mulk_i32 s1, 0xba3
	s_lshr_b32 s8, s1, 31
	s_ashr_i32 s1, s1, 18
	s_add_i32 s10, s1, s8
	s_mul_i32 s1, s10, 0x58
	s_sub_i32 s0, s0, s1
	s_sext_i32_i16 s0, s0
	s_lshl_b32 s1, s0, 6
	s_and_b32 s1, s1, 0xffffff00
	s_mul_i32 s8, s9, 0x1600
	s_add_i32 s1, s1, s8
	s_lshl_b32 s8, s0, 5
	s_and_b32 s0, s8, 0x60
	s_or_b32 s11, s1, s0
	s_and_b64 s[0:1], s[6:7], exec
	s_cselect_b32 s0, 0x80, 0
	s_or_b32 s0, s11, s0
	s_ashr_i32 s1, s0, 31
	s_lshl_b64 s[0:1], s[0:1], 10
	s_add_u32 s0, s88, s0
	s_sext_i32_i16 s10, s10
	s_addc_u32 s1, s89, s1
	s_lshl_b32 s11, s10, 6
	s_ashr_i32 s12, s11, 31
	s_add_u32 s0, s0, s11
	s_addc_u32 s1, s1, s12
	v_readlane_b32 s12, v253, 18
	v_readlane_b32 s13, v253, 19
	v_readlane_b32 s14, v253, 20
	v_readlane_b32 s15, v253, 21
	v_readlane_b32 s16, v253, 22
	v_readlane_b32 s17, v253, 23
	v_readlane_b32 s18, v253, 24
	v_readlane_b32 s19, v253, 25
	v_readlane_b32 s20, v253, 26
	v_readlane_b32 s21, v253, 27
	v_readlane_b32 s22, v253, 28
	v_readlane_b32 s23, v253, 29
	v_readlane_b32 s24, v253, 30
	v_readlane_b32 s25, v253, 31
	v_readlane_b32 s26, v253, 32
	v_readlane_b32 s27, v253, 33
	s_mov_b64 s[12:13], s[16:17]
	s_and_b64 s[6:7], s[6:7], exec
	s_mov_b64 s[14:15], s[18:19]
	s_mov_b64 s[16:17], s[20:21]
	s_mov_b64 s[18:19], s[22:23]
	s_mov_b64 s[20:21], s[24:25]
	s_cselect_b32 s7, s20, s18
	s_mul_hi_i32 s12, s9, 0xb00000
	s_mul_i32 s9, s9, 0xb00000
	s_cselect_b32 s6, s21, s19
	s_add_u32 s7, s7, s9
	s_addc_u32 s6, s6, s12
	s_mul_i32 s10, s10, 0xb0000
	s_mul_hi_i32 s9, s11, 0x2c00
	s_add_u32 s10, s7, s10
	s_addc_u32 s11, s6, s9
	s_ashr_i32 s9, s8, 31
	s_lshl_b64 s[6:7], s[8:9], 2
	v_and_b32_e32 v76, 31, v66
	s_add_u32 s6, s10, s6
	v_mov_b32_e32 v1, 0
	s_addc_u32 s7, s11, s7
	v_lshlrev_b32_e32 v0, 2, v76
	v_lshl_add_u64 v[12:13], s[6:7], 0, v[0:1]
	v_add_u32_e32 v30, 10, v69
	v_add_u32_e32 v31, 12, v69
	v_add_u32_e32 v32, 14, v69
	v_add_u32_e32 v33, 16, v69
	v_mad_i64_i32 v[14:15], s[6:7], v69, s5, v[12:13]
	v_add_u32_e32 v34, 18, v69
	v_add_u32_e32 v35, 20, v69
	v_add_u32_e32 v36, 22, v69
	v_add_u32_e32 v37, 24, v69
	v_add_u32_e32 v38, 26, v69
	v_add_u32_e32 v39, 28, v69
	v_add_u32_e32 v40, 30, v69
	v_add_u32_e32 v41, 32, v69
	v_mad_i64_i32 v[16:17], s[6:7], v16, s5, v[12:13]
	v_mad_i64_i32 v[18:19], s[6:7], v18, s5, v[12:13]
	v_mad_i64_i32 v[20:21], s[6:7], v20, s5, v[12:13]
	v_mad_i64_i32 v[22:23], s[6:7], v22, s5, v[12:13]
	v_mad_i64_i32 v[24:25], s[6:7], v30, s5, v[12:13]
	v_mad_i64_i32 v[26:27], s[6:7], v31, s5, v[12:13]
	v_mad_i64_i32 v[28:29], s[6:7], v32, s5, v[12:13]
	global_load_dword v78, v[14:15], off
	global_load_dword v79, v[16:17], off
	global_load_dword v80, v[18:19], off
	global_load_dword v81, v[20:21], off
	global_load_dword v82, v[22:23], off
	global_load_dword v84, v[24:25], off
	global_load_dword v83, v[26:27], off
	global_load_dword v85, v[28:29], off
	v_mad_i64_i32 v[14:15], s[6:7], v33, s5, v[12:13]
	v_add_u32_e32 v42, 34, v69
	v_add_u32_e32 v43, 36, v69
	v_add_u32_e32 v44, 38, v69
	v_add_u32_e32 v45, 40, v69
	v_add_u32_e32 v46, 42, v69
	v_add_u32_e32 v47, 44, v69
	v_add_u32_e32 v48, 46, v69
	v_add_u32_e32 v50, 48, v69
	v_mad_i64_i32 v[16:17], s[6:7], v34, s5, v[12:13]
	v_mad_i64_i32 v[18:19], s[6:7], v35, s5, v[12:13]
	v_mad_i64_i32 v[20:21], s[6:7], v36, s5, v[12:13]
	v_mad_i64_i32 v[22:23], s[6:7], v37, s5, v[12:13]
	v_mad_i64_i32 v[24:25], s[6:7], v38, s5, v[12:13]
	v_mad_i64_i32 v[26:27], s[6:7], v39, s5, v[12:13]
	v_mad_i64_i32 v[28:29], s[6:7], v40, s5, v[12:13]
	global_load_dword v86, v[14:15], off
	global_load_dword v88, v[16:17], off
	global_load_dword v87, v[18:19], off
	global_load_dword v89, v[20:21], off
	global_load_dword v90, v[22:23], off
	global_load_dword v92, v[24:25], off
	global_load_dword v91, v[26:27], off
	global_load_dword v93, v[28:29], off
	v_mad_i64_i32 v[14:15], s[6:7], v41, s5, v[12:13]
	v_add_u32_e32 v52, 50, v69
	v_add_u32_e32 v54, 52, v69
	v_add_u32_e32 v56, 54, v69
	v_add_u32_e32 v58, 56, v69
	v_add_u32_e32 v60, 58, v69
	v_add_u32_e32 v62, 60, v69
	v_add_u32_e32 v64, 62, v69
	v_mad_i64_i32 v[16:17], s[6:7], v42, s5, v[12:13]
	v_mad_i64_i32 v[18:19], s[6:7], v43, s5, v[12:13]
	v_mad_i64_i32 v[20:21], s[6:7], v44, s5, v[12:13]
	v_mad_i64_i32 v[22:23], s[6:7], v45, s5, v[12:13]
	v_mad_i64_i32 v[24:25], s[6:7], v46, s5, v[12:13]
	v_mad_i64_i32 v[26:27], s[6:7], v47, s5, v[12:13]
	v_mad_i64_i32 v[28:29], s[6:7], v48, s5, v[12:13]
	global_load_dword v94, v[14:15], off
	global_load_dword v96, v[16:17], off
	global_load_dword v95, v[18:19], off
	global_load_dword v97, v[20:21], off
	global_load_dword v98, v[22:23], off
	global_load_dword v100, v[24:25], off
	global_load_dword v99, v[26:27], off
	global_load_dword v101, v[28:29], off
	v_mad_i64_i32 v[14:15], s[6:7], v50, s5, v[12:13]
	v_mad_i64_i32 v[16:17], s[6:7], v52, s5, v[12:13]
	v_mad_i64_i32 v[18:19], s[6:7], v54, s5, v[12:13]
	v_mad_i64_i32 v[20:21], s[6:7], v56, s5, v[12:13]
	v_mad_i64_i32 v[22:23], s[6:7], v58, s5, v[12:13]
	v_mad_i64_i32 v[24:25], s[6:7], v60, s5, v[12:13]
	v_mad_i64_i32 v[26:27], s[6:7], v62, s5, v[12:13]
	v_mad_i64_i32 v[12:13], s[6:7], v64, s5, v[12:13]
	global_load_dword v102, v[14:15], off
	global_load_dword v104, v[16:17], off
	global_load_dword v103, v[18:19], off
	global_load_dword v105, v[20:21], off
	global_load_dword v106, v[22:23], off
	global_load_dword v108, v[24:25], off
	global_load_dword v107, v[26:27], off
	global_load_dword v109, v[12:13], off
	v_add_u32_e32 v110, s4, v0
	v_lshlrev_b32_e32 v0, 3, v66
	v_mad_i64_i32 v[12:13], s[6:7], v30, s5, 0
	v_mad_i64_i32 v[14:15], s[6:7], v31, s5, 0
	v_mad_i64_i32 v[16:17], s[6:7], v32, s5, 0
	v_mad_i64_i32 v[18:19], s[6:7], v33, s5, 0
	v_mad_i64_i32 v[20:21], s[6:7], v34, s5, 0
	v_mad_i64_i32 v[22:23], s[6:7], v35, s5, 0
	v_mad_i64_i32 v[24:25], s[6:7], v36, s5, 0
	v_mad_i64_i32 v[26:27], s[6:7], v37, s5, 0
	v_mad_i64_i32 v[28:29], s[6:7], v38, s5, 0
	v_mad_i64_i32 v[30:31], s[6:7], v39, s5, 0
	v_mad_i64_i32 v[32:33], s[6:7], v40, s5, 0
	v_mad_i64_i32 v[34:35], s[6:7], v41, s5, 0
	v_mad_i64_i32 v[36:37], s[6:7], v42, s5, 0
	v_mad_i64_i32 v[38:39], s[6:7], v43, s5, 0
	v_mad_i64_i32 v[40:41], s[6:7], v44, s5, 0
	v_mad_i64_i32 v[42:43], s[6:7], v45, s5, 0
	v_mad_i64_i32 v[44:45], s[6:7], v46, s5, 0
	v_mad_i64_i32 v[46:47], s[6:7], v47, s5, 0
	v_mad_i64_i32 v[48:49], s[6:7], v48, s5, 0
	v_mad_i64_i32 v[50:51], s[6:7], v50, s5, 0
	v_mad_i64_i32 v[52:53], s[6:7], v52, s5, 0
	v_mad_i64_i32 v[54:55], s[6:7], v54, s5, 0
	v_mad_i64_i32 v[56:57], s[6:7], v56, s5, 0
	v_mad_i64_i32 v[58:59], s[6:7], v58, s5, 0
	v_mad_i64_i32 v[60:61], s[6:7], v60, s5, 0
	v_mad_i64_i32 v[62:63], s[6:7], v62, s5, 0
	v_mad_i64_i32 v[64:65], s[6:7], v64, s5, 0
	v_ashrrev_i32_e32 v68, 3, v66
	v_and_b32_e32 v66, 56, v0
	s_movk_i32 s5, 0x84
	v_mul_u32_u24_e32 v0, 0x84, v66
	v_mul_lo_u32 v111, v69, s5
	v_lshlrev_b32_e32 v69, 2, v68
	v_add3_u32 v77, s4, v0, v69
	v_ashrrev_i32_e32 v69, 31, v68
	v_lshlrev_b64 v[68:69], 10, v[68:69]
	s_mov_b64 s[4:5], 0x2000
	v_lshl_add_u64 v[70:71], v[68:69], 0, s[4:5]
	s_mov_b64 s[4:5], 0x4000
	v_lshl_add_u64 v[72:73], v[68:69], 0, s[4:5]
	s_mov_b64 s[4:5], 0x6000
	v_mov_b32_e32 v67, v1
	v_lshl_add_u64 v[74:75], v[68:69], 0, s[4:5]
	v_lshlrev_b32_e32 v0, 2, v76
	v_add_u32_e32 v76, v110, v111
	s_mov_b32 s8, s80
	s_mov_b64 s[4:5], s[0:1]
	s_mov_b64 s[22:23], s[26:27]
	s_branch .LBB0_710

.LBB0_712:
	s_cmp_eq_u32 s69, 2
	s_cbranch_scc1 .Lswap_done
	s_lshl_b32 s0, s72, 5
	s_and_b32 s68, s0, 0x60
	s_lshl_b32 s74, s68, 7
	v_mov_b32_e32 v0, v174
	v_mov_b32_e32 v8, v174
	s_cmpk_gt_i32 s87, 0x2ff
	s_barrier
	s_cbranch_scc1 .LBB0_732
	v_add_u32_e32 v0, s33, v8
	v_lshlrev_b32_e32 v1, 4, v0
	v_add_u32_e32 v2, 0x2000, v1
	v_ashrrev_i32_e32 v3, 31, v2
	v_lshrrev_b32_e32 v3, 22, v3
	v_add_u32_e32 v3, v2, v3
	v_ashrrev_i32_e32 v3, 10, v3
	v_mul_i32_i24_e32 v5, 0x400, v3
	v_sub_u32_e32 v2, v2, v5
	v_lshrrev_b32_e32 v5, 4, v2
	v_bitop3_b32 v2, v5, v2, 32 bitop3:0x6c
	v_ashrrev_i32_e32 v5, 31, v2
	v_lshrrev_b32_e32 v5, 26, v5
	v_add_u32_e32 v5, v2, v5
	v_lshrrev_b32_e32 v6, 6, v5
	v_and_b32_e32 v5, 0xc0, v5
	v_lshlrev_b32_e32 v4, 5, v3
	v_sub_u32_e32 v2, v2, v5
	v_mov_b32_e32 v175, 1
	v_lshlrev_b32_e32 v3, 3, v3
	v_and_b32_e32 v4, 32, v4
	v_ashrrev_i16_sdwa v2, v175, sext(v2) dst_sel:DWORD dst_unused:UNUSED_PAD src0_sel:DWORD src1_sel:BYTE_0
	v_and_b32_e32 v3, 0x1ffff0, v3
	v_add_u32_sdwa v2, v4, sext(v2) dst_sel:DWORD dst_unused:UNUSED_PAD src0_sel:DWORD src1_sel:WORD_0
	v_add_lshl_u32 v3, v6, v3, 11
	v_lshl_add_u32 v160, v2, 1, v3
	v_ashrrev_i32_e32 v2, 31, v0
	v_lshrrev_b32_e32 v2, 26, v2
	v_add_u32_e32 v2, v0, v2
	v_bfe_i32 v0, v0, 27, 1
	v_lshrrev_b32_e32 v0, 22, v0
	v_add_u32_e32 v0, v1, v0
	v_and_b32_e32 v0, 0xfffffc00, v0
	v_sub_u32_e32 v0, v1, v0
	v_lshrrev_b32_e32 v1, 4, v0
	v_bitop3_b32 v0, v1, v0, 32 bitop3:0x6c
	v_ashrrev_i32_e32 v1, 31, v0
	v_lshrrev_b32_e32 v1, 26, v1
	v_add_u32_e32 v1, v0, v1
	v_ashrrev_i32_e32 v2, 6, v2
	v_lshrrev_b32_e32 v4, 6, v1
	v_and_b32_e32 v1, 0xc0, v1
	v_lshlrev_b32_e32 v3, 5, v2
	v_sub_u32_e32 v0, v0, v1
	v_lshlrev_b32_e32 v1, 3, v2
	v_and_b32_e32 v3, 32, v3
	v_ashrrev_i16_sdwa v0, v175, sext(v0) dst_sel:DWORD dst_unused:UNUSED_PAD src0_sel:DWORD src1_sel:BYTE_0
	v_and_b32_e32 v1, 0x1ffff0, v1
	v_add_u32_sdwa v0, v3, sext(v0) dst_sel:DWORD dst_unused:UNUSED_PAD src0_sel:DWORD src1_sel:WORD_0
	v_add_lshl_u32 v1, v4, v1, 11
	v_lshl_add_u32 v162, v0, 1, v1
	v_mov_b32_e32 v0, v174
	s_add_u32 s13, s66, 0x600000
	v_add_u32_e32 v0, s33, v0
	v_ashrrev_i32_e32 v2, 31, v0
	v_lshrrev_b32_e32 v2, 26, v2
	v_lshlrev_b32_e32 v1, 4, v0
	v_add_u32_e32 v2, v0, v2
	v_bfe_i32 v0, v0, 27, 1
	v_lshrrev_b32_e32 v0, 22, v0
	s_addc_u32 s26, s67, 0
	s_ashr_i32 s0, s87, 31
	v_add_u32_e32 v0, v1, v0
	s_lshr_b32 s0, s0, 29
	v_and_b32_e32 v0, 0xfffffc00, v0
	s_add_i32 s0, s87, s0
	v_sub_u32_e32 v0, v1, v0
	s_and_b32 s1, s0, -8
	v_lshrrev_b32_e32 v3, 4, v0
	s_sub_i32 s1, s87, s1
	v_bitop3_b32 v0, v3, v0, 32 bitop3:0x6c
	s_cmp_lt_i32 s1, 0
	s_movk_i32 s4, 0x61
	v_ashrrev_i32_e32 v4, 31, v0
	s_cselect_b32 s4, s4, 0x60
	v_lshrrev_b32_e32 v4, 26, v4
	s_mul_i32 s1, s1, s4
	s_ashr_i32 s0, s0, 3
	v_add_u32_e32 v4, v0, v4
	s_add_i32 s0, s1, s0
	v_ashrrev_i32_e32 v5, 6, v4
	v_and_b32_e32 v4, 0xc0, v4
	v_add_u32_e32 v1, 0x2000, v1
	s_ashr_i32 s1, s0, 31
	v_sub_u32_e32 v0, v0, v4
	v_ashrrev_i32_e32 v4, 31, v1
	s_lshr_b32 s1, s1, 27
	v_ashrrev_i32_e32 v2, 6, v2
	v_lshrrev_b32_e32 v4, 22, v4
	s_add_i32 s1, s0, s1
	v_lshlrev_b32_e32 v3, 3, v2
	v_add_u32_e32 v4, v1, v4
	s_ashr_i32 s4, s1, 5
	s_andn2_b32 s1, s1, 31
	v_and_b32_e32 v3, -16, v3
	v_ashrrev_i32_e32 v4, 10, v4
	s_sub_i32 s1, s0, s1
	v_add_u32_e32 v3, v5, v3
	v_mul_i32_i24_e32 v5, 0x400, v4
	s_bfe_i32 s0, s1, 0x80000
	v_sub_u32_e32 v1, v1, v5
	s_bfe_u32 s0, s0, 0x3000c
	v_lshrrev_b32_e32 v5, 4, v1
	s_add_i32 s5, s1, s0
	v_bitop3_b32 v1, v5, v1, 32 bitop3:0x6c
	s_bfe_i32 s0, s5, 0x80000
	s_and_b32 s5, s5, 0xf8
	v_ashrrev_i32_e32 v6, 31, v1
	s_sub_i32 s1, s1, s5
	v_lshrrev_b32_e32 v6, 26, v6
	s_lshl_b32 s4, s4, 3
	s_sext_i32_i8 s1, s1
	v_lshlrev_b32_e32 v5, 3, v4
	v_add_u32_e32 v6, v1, v6
	s_add_i32 s44, s4, s1
	v_lshlrev_b32_e32 v2, 5, v2
	v_ashrrev_i16_sdwa v0, v175, sext(v0) dst_sel:DWORD dst_unused:UNUSED_PAD src0_sel:DWORD src1_sel:BYTE_0
	v_and_b32_e32 v5, -16, v5
	v_ashrrev_i32_e32 v7, 6, v6
	s_sext_i32_i16 s0, s0
	v_and_b32_e32 v2, 32, v2
	v_bfe_i32 v0, v0, 0, 16
	v_add_u32_e32 v5, v7, v5
	v_and_b32_e32 v6, 0xc0, v6
	s_lshl_b32 s1, s44, 8
	s_lshr_b32 s0, s0, 3
	v_sub_u32_e32 v1, v1, v6
	v_add_u32_e32 v6, s1, v3
	v_add_lshl_u32 v0, v2, v0, 1
	v_add_u32_e32 v2, s1, v5
	s_bitset1_b32 s1, 7
	s_bfe_i64 s[4:5], s[0:1], 0x100000
	s_lshl_b64 s[4:5], s[4:5], 19
	s_add_u32 s20, s13, s4
	s_addc_u32 s21, s26, s5
	s_add_i32 s27, s84, 0
	s_add_i32 s28, s27, 0x10000
	s_add_i32 s29, s27, 0x12000
	s_mov_b32 m0, s28
	s_add_u32 s4, s20, 0x40000
	global_load_lds_dwordx4 v162, s[20:21]
	s_mov_b32 m0, s29
	s_addc_u32 s5, s21, 0
	s_add_i32 s30, s27, 0x14000
	v_lshlrev_b32_e32 v4, 5, v4
	v_ashrrev_i16_sdwa v1, v175, sext(v1) dst_sel:DWORD dst_unused:UNUSED_PAD src0_sel:DWORD src1_sel:BYTE_0
	global_load_lds_dwordx4 v160, s[20:21]
	s_mov_b32 m0, s30
	s_add_i32 s31, s27, 0x16000
	v_and_b32_e32 v4, 32, v4
	v_bfe_i32 v1, v1, 0, 16
	global_load_lds_dwordx4 v162, s[4:5]
	s_mov_b32 m0, s31
	v_add_lshl_u32 v1, v4, v1, 1
	global_load_lds_dwordx4 v160, s[4:5]
	v_lshl_add_u32 v164, v6, 11, v0
	s_mov_b32 m0, s27
	s_add_i32 s34, s27, 0x2000
	v_add_u32_e32 v3, s1, v3
	v_lshl_add_u32 v166, v2, 11, v1
	global_load_lds_dwordx4 v164, s[2:3]
	s_mov_b32 m0, s34
	s_add_i32 s35, s27, 0x4000
	v_add_u32_e32 v4, s1, v5
	v_lshl_add_u32 v168, v3, 11, v0
	global_load_lds_dwordx4 v166, s[2:3]
	s_mov_b32 m0, s35
	s_add_i32 s36, s27, 0x6000
	v_lshl_add_u32 v170, v4, 11, v1
	global_load_lds_dwordx4 v168, s[2:3]
	s_mov_b32 m0, s36
	v_mov_b32_e32 v165, 0
	global_load_lds_dwordx4 v170, s[2:3]
	v_readlane_b32 s6, v253, 37
	v_mov_b32_e32 v163, v165
	v_mov_b32_e32 v161, v165
	v_mov_b32_e32 v167, v165
	s_cmp_eq_u32 s6, 1
	s_mov_b32 s1, 0
	v_lshl_add_u64 v[6:7], s[20:21], 0, v[162:163]
	v_lshl_add_u64 v[4:5], s[20:21], 0, v[160:161]
	v_lshl_add_u64 v[0:1], s[2:3], 0, v[164:165]
	s_cselect_b64 s[4:5], -1, 0
	s_cmp_lg_u32 s6, 1
	v_lshl_add_u64 v[2:3], s[2:3], 0, v[166:167]
	s_cbranch_scc1 .LBB0_715
	s_barrier

.LBB0_732:
	s_cmp_eq_u32 s69, 1
	s_cbranch_scc0 .Lswap_done
	s_mov_b32 s69, 2
	v_mov_b32_e32 v66, v174
	s_branch .Lguw_entry
